# sample S5 tile loop (spatial blocks): the per-tile vmcnt(0) that also waited for the previous tile's YB store acks moved into the initial-state path / loop entry; prompt tile loop: next-tile loads iss
# speedup vs baseline: 1.0091x; 1.0006x over previous
.LBB0_426:
	s_lshl_b32 s28, s7, 7
	v_or_b32_e32 v0, s28, v143
	v_readlane_b32 s30, v254, 20
	v_lshlrev_b32_e32 v0, 2, v0
	v_or_b32_e32 v1, s28, v142
	v_readlane_b32 s31, v254, 21
	v_lshl_or_b32 v1, v1, 5, v92
	s_nop 3
	global_load_dwordx2 v[100:101], v0, s[30:31]
	global_load_dwordx4 v[32:35], v1, s[76:77]
	global_load_dwordx4 v[36:39], v1, s[76:77] offset:1024
	global_load_dwordx4 v[40:43], v1, s[76:77] offset:2048
	v_lshl_or_b32 v0, s7, 12, v157
	s_lshl_b32 s28, s7, 6
	global_load_dwordx4 v[44:47], v1, s[76:77] offset:3072
	global_load_dwordx4 v[48:51], v0, s[78:79]
	global_load_dwordx4 v[52:55], v0, s[78:79] offset:64
	global_load_dwordx4 v[56:59], v0, s[78:79] offset:128
	global_load_dwordx4 v[60:63], v0, s[78:79] offset:192
	v_lshl_add_u64 v[0:1], v[96:97], 0, s[28:29]
	global_load_dwordx4 v[64:67], v[0:1], off
	v_add_u32_e32 v0, s3, v142
	v_ashrrev_i32_e32 v1, 31, v0
	v_add_u32_e32 v102, s3, v210
	v_lshlrev_b64 v[0:1], 12, v[0:1]
	v_ashrrev_i32_e32 v103, 31, v102
	v_lshl_add_u64 v[0:1], s[20:21], 0, v[0:1]
	s_lshl_b32 s28, s7, 5
	v_lshlrev_b64 v[2:3], 12, v[102:103]
	v_lshl_add_u64 v[0:1], v[0:1], 0, s[28:29]
	v_lshl_add_u64 v[2:3], s[20:21], 0, v[2:3]
	v_lshl_add_u64 v[0:1], v[0:1], 0, v[92:93]
	v_lshl_add_u64 v[2:3], v[2:3], 0, s[28:29]
	v_lshl_add_u64 v[2:3], v[2:3], 0, v[94:95]
	global_load_dwordx4 v[68:71], v[0:1], off
	global_load_dwordx2 v[130:131], v[2:3], off
	v_add_u32_e32 v0, 16, v102
	v_ashrrev_i32_e32 v1, 31, v0
	v_lshlrev_b64 v[0:1], 12, v[0:1]
	v_lshl_add_u64 v[0:1], s[20:21], 0, v[0:1]
	v_lshl_add_u64 v[0:1], v[0:1], 0, s[28:29]
	v_lshl_add_u64 v[0:1], v[0:1], 0, v[94:95]
	global_load_dwordx2 v[126:127], v[0:1], off
	s_and_b32 s33, s70, 0x7f
	s_mov_b32 s7, s29
	s_add_u32 s60, s20, s28
	v_lshl_or_b32 v4, s33, 8, v178
	s_addc_u32 s61, s21, 0
	s_lshl_b64 s[6:7], s[6:7], 15
	v_lshl_add_u64 v[0:1], s[48:49], 0, v[178:179]
	v_lshl_add_u64 v[2:3], s[50:51], 0, v[178:179]
	v_or_b32_e32 v4, s6, v4
	v_mov_b32_e32 v5, s7
	v_mov_b32_e32 v136, 0
	s_mov_b32 s80, 1
	v_add_u32_e32 v104, s3, v144
	v_add_u32_e32 v106, s3, v152
	v_lshl_add_u64 v[108:109], v[98:99], 0, s[28:29]
	s_lshl_b32 s28, s11, 17
	v_lshl_add_u64 v[110:111], s[60:61], 0, v[92:93]
	v_lshl_add_u64 v[112:113], s[60:61], 0, v[94:95]
	v_lshl_add_u64 v[114:115], v[0:1], 0, s[6:7]
	v_lshl_add_u64 v[116:117], v[2:3], 0, s[6:7]
	v_lshl_add_u64 v[118:119], s[16:17], 0, v[4:5]
	v_lshl_add_u64 v[120:121], s[18:19], 0, v[4:5]
	s_mov_b64 s[60:61], 0
	v_mov_b32_e32 v137, v136
	s_waitcnt vmcnt(12)
	v_xor_b32_e32 v122, 0x80000000, v101
	v_mov_b32_e32 v123, v101
	v_mov_b32_e32 v124, v100
	v_mov_b32_e32 v125, v100
	v_pk_mov_b32 v[128:129], v[122:123], v[122:123] op_sel:[1,0]
	s_waitcnt vmcnt(0)
	s_branch .LBB0_428

.LBB0_428:
	v_cndmask_b32_e64 v0, 0, 1, s[4:5]
	v_cmp_ne_u32_e64 s[6:7], 1, v0
	s_andn2_b64 vcc, exec, s[4:5]
	v_mov_b32_e32 v138, 0
	v_mov_b32_e32 v163, 0
	v_mov_b32_e32 v161, 0
	v_mov_b32_e32 v159, 0
	v_mov_b32_e32 v139, 0
	v_mov_b32_e32 v162, 0
	v_mov_b32_e32 v160, 0
	v_mov_b32_e32 v103, 0
	s_cbranch_vccnz .LBB0_430
	v_lshl_add_u64 v[0:1], v[118:119], 0, s[60:61]
	v_add_co_u32_e32 v4, vcc, 0x8000, v0
	v_lshl_add_u64 v[2:3], v[120:121], 0, s[60:61]
	s_nop 0
	v_addc_co_u32_e32 v5, vcc, 0, v1, vcc
	global_load_dword v162, v[4:5], off
	v_add_co_u32_e32 v4, vcc, 0x8000, v2
	global_load_dword v139, v[0:1], off
	s_nop 0
	v_addc_co_u32_e32 v5, vcc, 0, v3, vcc
	global_load_dword v163, v[4:5], off
	v_add_co_u32_e32 v4, vcc, 0x10000, v0
	global_load_dword v138, v[2:3], off
	s_nop 0
	v_addc_co_u32_e32 v5, vcc, 0, v1, vcc
	global_load_dword v160, v[4:5], off
	v_add_co_u32_e32 v4, vcc, 0x10000, v2
	s_nop 1
	v_addc_co_u32_e32 v5, vcc, 0, v3, vcc
	v_add_co_u32_e32 v0, vcc, 0x18000, v0
	global_load_dword v161, v[4:5], off
	s_nop 0
	v_addc_co_u32_e32 v1, vcc, 0, v1, vcc
	global_load_dword v103, v[0:1], off
	v_add_co_u32_e32 v0, vcc, 0x18000, v2
	s_nop 1
	v_addc_co_u32_e32 v1, vcc, 0, v3, vcc
	global_load_dword v159, v[0:1], off
	s_waitcnt vmcnt(0)
.LBB0_430:
	s_waitcnt vmcnt(2)
	v_mfma_f32_32x32x16_bf16 v[16:31], v[32:35], v[68:71], 0
	s_cmp_ge_u32 s80, s11
	v_add_u32_e32 v158, 32, v102
	v_mov_b64_e32 v[134:135], v[126:127]
	v_mov_b64_e32 v[132:133], v[130:131]
	v_mfma_f32_32x32x16_bf16 v[0:15], v[36:39], v[68:71], 0
	s_nop 5
	ds_write_b128 v153, v[16:19]
	ds_write_b128 v153, v[20:23] offset:32
	ds_write_b128 v153, v[24:27] offset:64
	ds_write_b128 v153, v[28:31] offset:96
	s_nop 1
	ds_write_b128 v153, v[0:3] offset:128
	v_mfma_f32_32x32x16_bf16 v[16:31], v[40:43], v[68:71], 0
	ds_write_b128 v153, v[4:7] offset:160
	ds_write_b128 v153, v[8:11] offset:192
	ds_write_b128 v153, v[12:15] offset:224
	s_nop 8
	ds_write_b128 v153, v[16:19] offset:256
	ds_write_b128 v153, v[20:23] offset:288
	ds_write_b128 v153, v[24:27] offset:320
	ds_write_b128 v153, v[28:31] offset:352
	v_mfma_f32_32x32x16_bf16 v[0:15], v[44:47], v[68:71], 0
	s_nop 11
	ds_write_b128 v153, v[0:3] offset:384
	ds_write_b128 v153, v[4:7] offset:416
	ds_write_b128 v153, v[8:11] offset:448
	ds_write_b128 v153, v[12:15] offset:480
	s_cbranch_scc1 .LBB0_432
	v_ashrrev_i32_e32 v107, 31, v106
	v_add_u32_e32 v2, 32, v102
	v_lshlrev_b64 v[0:1], 12, v[106:107]
	v_ashrrev_i32_e32 v3, 31, v2
	v_lshl_add_u64 v[0:1], v[110:111], 0, v[0:1]
	v_lshlrev_b64 v[2:3], 12, v[2:3]
	v_ashrrev_i32_e32 v105, 31, v104
	v_lshl_add_u64 v[2:3], v[112:113], 0, v[2:3]
	global_load_dwordx4 v[68:71], v[0:1], off
	global_load_dwordx2 v[132:133], v[2:3], off
	v_lshlrev_b64 v[0:1], 12, v[104:105]
	v_lshl_add_u64 v[0:1], v[112:113], 0, v[0:1]
	global_load_dwordx2 v[134:135], v[0:1], off

.Ls5p_tile:
	v_mfma_f32_32x32x16_bf16 v[0:15], v[68:71], v[32:35], 0
	v_mfma_f32_32x32x16_bf16 v[112:127], v[68:71], v[40:43], 0
	s_cmp_lt_u32 s6, 63
	s_cbranch_scc0 .Ls5p_m3
	global_load_dwordx2 v[190:191], v[232:233], off
	global_load_dwordx2 v[192:193], v[234:235], off
	v_lshl_add_u64 v[232:233], v[232:233], 0, s[50:51]
	v_lshl_add_u64 v[234:235], v[234:235], 0, s[50:51]
.Ls5p_m3:
	v_mfma_f32_32x32x16_bf16 v[16:31], v[68:71], v[36:39], 0
	s_nop 7
